# no L1 invalidate at the barriers after the in-GEMM and after the out-GEMM (the next phase reads nothing this CU loaded since the previous barrier's invalidate)
# speedup vs baseline: 1.0066x; 1.0064x over previous
; DI unsigned xb_ld(unsigned* p) { return __hip_atomic_load(p, __ATOMIC_RELAXED, __HIP_MEMORY_SCOPE_AGENT); }
; DI unsigned xb_add(unsigned* p, unsigned v) { return __hip_atomic_fetch_add(p, v, __ATOMIC_RELAXED, __HIP_MEMORY_SCOPE_AGENT); }
; #define XB_SPIN(cond, bar) do { unsigned _sp = 0; while (cond) { __builtin_amdgcn_s_sleep(1); \
;     if ((++_sp & 255u) == 0u) { if (xb_ld(&(bar)[XB_TMO])) break; if (_sp > XB_SPIN_CAP) { atomicAdd(&(bar)[XB_TMO], 1u); break; } } } } while (0)
; DI void xcd_barrier(const XcdBarrier& b) {
;     ...
;       const unsigned tg = og / nx;
;       if (og + 1u == (tg + 1u) * nx) xb_add(&bar[XB_TOPGEN], 1u);
;       else XB_SPIN(xb_ld(&bar[XB_TOPGEN]) == tg, bar);
;       __builtin_amdgcn_fence(__ATOMIC_ACQUIRE, "agent");
;       xb_add(&bar[XB_XGEN(b.x)], 1u);
;       asm volatile("s_waitcnt vmcnt(0)" ::: "memory");
;     } else {
;       XB_SPIN(xb_ld(&bar[XB_XGEN(b.x)]) == gen, bar);
;       __builtin_amdgcn_fence(__ATOMIC_ACQUIRE, "agent");
;       asm volatile("s_waitcnt vmcnt(0)" ::: "memory");
.Lsy1_inv:
.Lsy1_poll:
	global_load_dword v5, v6, s[88:89] sc1
	s_waitcnt vmcnt(0)
	v_readfirstlane_b32 s10, v5
	s_sub_i32 s10, s10, s9
	s_cmp_ge_i32 s10, 0
	s_cbranch_scc1 .Lsy1_done
	s_add_i32 s11, s11, 1
	s_sleep 1
	s_cmp_lt_u32 s11, 0x400000
	s_cbranch_scc1 .Lsy1_poll

; DI unsigned xb_ld(unsigned* p) { return __hip_atomic_load(p, __ATOMIC_RELAXED, __HIP_MEMORY_SCOPE_AGENT); }
; DI unsigned xb_add(unsigned* p, unsigned v) { return __hip_atomic_fetch_add(p, v, __ATOMIC_RELAXED, __HIP_MEMORY_SCOPE_AGENT); }
; #define XB_SPIN(cond, bar) do { unsigned _sp = 0; while (cond) { __builtin_amdgcn_s_sleep(1); \
;     if ((++_sp & 255u) == 0u) { if (xb_ld(&(bar)[XB_TMO])) break; if (_sp > XB_SPIN_CAP) { atomicAdd(&(bar)[XB_TMO], 1u); break; } } } } while (0)
; DI void xcd_barrier(const XcdBarrier& b) {
;     ...
;       const unsigned tg = og / nx;
;       if (og + 1u == (tg + 1u) * nx) xb_add(&bar[XB_TOPGEN], 1u);
;       else XB_SPIN(xb_ld(&bar[XB_TOPGEN]) == tg, bar);
;       __builtin_amdgcn_fence(__ATOMIC_ACQUIRE, "agent");
;       xb_add(&bar[XB_XGEN(b.x)], 1u);
;       asm volatile("s_waitcnt vmcnt(0)" ::: "memory");
;     } else {
;       XB_SPIN(xb_ld(&bar[XB_XGEN(b.x)]) == gen, bar);
;       __builtin_amdgcn_fence(__ATOMIC_ACQUIRE, "agent");
;       asm volatile("s_waitcnt vmcnt(0)" ::: "memory");
.Lsy5_inv:
.Lsy5_poll:
	global_load_dword v4, v5, s[88:89] sc1
	s_waitcnt vmcnt(0)
	v_readfirstlane_b32 s16, v4
	s_sub_i32 s16, s16, s15
	s_cmp_ge_i32 s16, 0
	s_cbranch_scc1 .Lsy5_done
	s_add_i32 s17, s17, 1
	s_sleep 1
	s_cmp_lt_u32 s17, 0x400000
	s_cbranch_scc1 .Lsy5_poll

; DI unsigned xb_ld(unsigned* p) { return __hip_atomic_load(p, __ATOMIC_RELAXED, __HIP_MEMORY_SCOPE_AGENT); }
; DI unsigned xb_add(unsigned* p, unsigned v) { return __hip_atomic_fetch_add(p, v, __ATOMIC_RELAXED, __HIP_MEMORY_SCOPE_AGENT); }
; #define XB_SPIN(cond, bar) do { unsigned _sp = 0; while (cond) { __builtin_amdgcn_s_sleep(1); \
;     if ((++_sp & 255u) == 0u) { if (xb_ld(&(bar)[XB_TMO])) break; if (_sp > XB_SPIN_CAP) { atomicAdd(&(bar)[XB_TMO], 1u); break; } } } } while (0)
; DI void xcd_barrier(const XcdBarrier& b) {
;     ...
;       const unsigned tg = og / nx;
;       if (og + 1u == (tg + 1u) * nx) xb_add(&bar[XB_TOPGEN], 1u);
;       else XB_SPIN(xb_ld(&bar[XB_TOPGEN]) == tg, bar);
;       __builtin_amdgcn_fence(__ATOMIC_ACQUIRE, "agent");
;       xb_add(&bar[XB_XGEN(b.x)], 1u);
;       asm volatile("s_waitcnt vmcnt(0)" ::: "memory");
;     } else {
;       XB_SPIN(xb_ld(&bar[XB_XGEN(b.x)]) == gen, bar);
;       __builtin_amdgcn_fence(__ATOMIC_ACQUIRE, "agent");
;       asm volatile("s_waitcnt vmcnt(0)" ::: "memory");
.Lsy9_inv:
.Lsy9_poll:
	global_load_dword v5, v6, s[88:89] sc1
	s_waitcnt vmcnt(0)
	v_readfirstlane_b32 s14, v5
	s_sub_i32 s14, s14, s12
	s_cmp_ge_i32 s14, 0
	s_cbranch_scc1 .Lsy9_done
	s_add_i32 s20, s20, 1
	s_sleep 1
	s_cmp_lt_u32 s20, 0x400000
	s_cbranch_scc1 .Lsy9_poll
